# hand-written row-pipelined EpiRes epilogue: G in regs, B folded into acc, saddr addressing, counted vmcnt
# speedup vs baseline: 1.0042x; 1.0042x over previous
; template <class Epi>
; __device__ __forceinline__ void gemm_phase(LAS unsigned char* lds, const Gemm g, const StaticOrder& S, const Epi& E, int wv) {
;     ...
;         if (!has_next) break;
; #pragma unroll
;         for (int a = 0; a < 2; ++a)
; #pragma unroll
;             for (int b = 0; b < 2; ++b)
; #pragma unroll
;                 for (int m = 0; m < 4; ++m)
; #pragma unroll
;                     for (int n = 0; n < 2; ++n) acc[a][b][m][n] = (f32x4){0.f, 0.f, 0.f, 0.f};
;         cur = nxt; cA = nA; cB = nB; ++ui;
.LBB0_416:
	s_and_b64 vcc, exec, s[6:7]
	s_mov_b32 s77, s58
	s_mov_b32 s78, s60
	s_mov_b64 s[64:65], s[68:69]
	s_mov_b64 s[70:71], s[62:63]
	s_cbranch_vccnz .LBB0_507

; #define PG8_STAGE(bufoff, gbase, voff) do { _Pragma("unroll") for (int _i = 0; _i < 2; ++_i) \
;         __builtin_amdgcn_global_load_lds((const unsigned*)((const char*)(gbase) + (voff)[_i]), (LAS unsigned*)(lds + (bufoff) + ldsw + _i * 8192), 16, 0, 0); } while (0)
; #define PG8_LDA(dst, b, h) do { _Pragma("unroll") for (int m = 0; m < 4; ++m) _Pragma("unroll") for (int k = 0; k < 2; ++k) dst[m][k] = *(const LAS bf16x8*)(lds + PG8_SA(b, h) + aoff + m * 2048 + k * 1024); } while (0)
; #define PG8_LDB(dst, b, h) do { _Pragma("unroll") for (int n = 0; n < 2; ++n) _Pragma("unroll") for (int k = 0; k < 2; ++k) dst[n][k] = *(const LAS bf16x8*)(lds + PG8_SB(b, h) + boff + n * 2048 + k * 1024); } while (0)
; #define PG8_MMA(ai, bj, At, Bt) do { __builtin_amdgcn_s_setprio(1); _Pragma("unroll") for (int m = 0; m < 4; ++m) _Pragma("unroll") for (int n = 0; n < 2; ++n) _Pragma("unroll") for (int k = 0; k < 2; ++k) \
;         acc[ai][bj][m][n] = __builtin_amdgcn_mfma_f32_16x16x32_bf16(Bt[n][k], At[m][k], acc[ai][bj][m][n], 0, 0, 0); __builtin_amdgcn_s_setprio(0); } while (0)
; #define PG8_WAIT_L(n) asm volatile("s_waitcnt lgkmcnt(" #n ")" ::: "memory")
; #define PG8_BAR __builtin_amdgcn_s_barrier()
; #define PG8_SCHED __builtin_amdgcn_sched_barrier(0)
; template <class Epi>
; __device__ __forceinline__ void gemm_phase(LAS unsigned char* lds, const Gemm g, const StaticOrder& S, const Epi& E, int wv) {
;     ...
;         for (int t = 0; t < nt; t += 2) {
;             const bool last = (t == nt - 2);
;             const char* a1 = cA + (size_t)(t + 1) * kstep;
;             const char* a2 = last ? nA : cA + (size_t)(t + 2) * kstep; const char* b2 = last ? nB : cB + (size_t)(t + 2) * kstep;
;             const char* a3 = a2 + kstep; const char* b3 = b2 + kstep;
;             PG8_LDB(B0, 0, 0); PG8_SCHED; PG8_LDA(At, 0, 0); PG8_STAGE(PG8_SA(1, 1), a1 + hstep, voffA);
;             PG8_WAIT_L(8); PG8_BAR; PG8_WAIT_L(0); PG8_MMA(0, 0, At, B0); PG8_BAR; PG8_SCHED;
;             PG8_LDB(B1, 0, 1); PG8_STAGE(PG8_SB(0, 0), b2, voffB);
;             PG8_BAR; PG8_WAIT_L(0); PG8_MMA(0, 1, At, B1); PG8_BAR;
;             PG8_LDA(At, 0, 1); PG8_STAGE(PG8_SA(0, 0), a2, voffA);
;             PG8_BAR; PG8_WAIT_L(0); PG8_MMA(1, 0, At, B0); PG8_BAR; PG8_SCHED;
.LBB0_424:
	s_add_u32 s64, s8, 0xfff80080
	s_addc_u32 s65, s9, -1
	s_add_i32 s96, 0, 0x10000
	v_add_u32_e32 v140, s96, v192
	ds_read_b128 v[128:131], v140
	ds_read_b128 v[132:135], v140 offset:1024
	ds_read_b128 v[136:139], v140 offset:2048
	ds_read_b128 v[140:143], v140 offset:3072
	s_cmp_eq_u32 s86, 28
	s_cselect_b32 s71, s34, s65
	s_cselect_b32 s70, s35, s64
	s_cselect_b32 s65, s59, s85
	s_cselect_b32 s64, s61, s79
	v_lshl_add_u64 v[182:183], s[8:9], 0, v[166:167]
	s_add_i32 m0, s24, 0xc000
	ds_read_b128 v[144:147], v193
	ds_read_b128 v[148:151], v193 offset:1024
	ds_read_b128 v[152:155], v193 offset:2048
	ds_read_b128 v[156:159], v193 offset:3072
	ds_read_b128 v[160:163], v193 offset:4096
	ds_read_b128 v[170:173], v193 offset:5120
	ds_read_b128 v[174:177], v193 offset:6144
	ds_read_b128 v[178:181], v193 offset:7168
	global_load_lds_dwordx4 v[182:183], off
	v_lshl_add_u64 v[182:183], s[8:9], 0, v[168:169]
	s_add_i32 m0, s24, 0xe000
	s_nop 0
	global_load_lds_dwordx4 v[182:183], off
	s_waitcnt lgkmcnt(8)
	s_barrier
	s_waitcnt lgkmcnt(0)
	s_setprio 1
	s_waitcnt lgkmcnt(0)
	v_mfma_f32_16x16x32_bf16 v[124:127], v[128:131], v[144:147], v[124:127]
	v_mfma_f32_16x16x32_bf16 v[120:123], v[136:139], v[144:147], v[120:123]
	v_mfma_f32_16x16x32_bf16 v[108:111], v[128:131], v[152:155], v[108:111]
	v_mfma_f32_16x16x32_bf16 v[104:107], v[136:139], v[152:155], v[104:107]
	v_mfma_f32_16x16x32_bf16 v[92:95], v[128:131], v[160:163], v[92:95]
	v_mfma_f32_16x16x32_bf16 v[88:91], v[136:139], v[160:163], v[88:91]
	v_mfma_f32_16x16x32_bf16 v[76:79], v[128:131], v[174:177], v[76:79]
	v_mfma_f32_16x16x32_bf16 v[72:75], v[136:139], v[174:177], v[72:75]
	v_mfma_f32_16x16x32_bf16 v[124:127], v[132:135], v[148:151], v[124:127]
	v_mfma_f32_16x16x32_bf16 v[120:123], v[140:143], v[148:151], v[120:123]
	v_mfma_f32_16x16x32_bf16 v[108:111], v[132:135], v[156:159], v[108:111]
	v_mfma_f32_16x16x32_bf16 v[104:107], v[140:143], v[156:159], v[104:107]
	v_mfma_f32_16x16x32_bf16 v[92:95], v[132:135], v[170:173], v[92:95]
	v_mfma_f32_16x16x32_bf16 v[88:91], v[140:143], v[170:173], v[88:91]
	v_mfma_f32_16x16x32_bf16 v[76:79], v[132:135], v[178:181], v[76:79]
	v_mfma_f32_16x16x32_bf16 v[72:75], v[140:143], v[178:181], v[72:75]
	s_setprio 0
	s_barrier
	s_add_i32 vcc_lo, 0, 0x14000
	v_add_u32_e32 v190, vcc_lo, v192
	s_add_i32 s96, s96, s37
	ds_read_b128 v[182:185], v190
	ds_read_b128 v[186:189], v190 offset:1024
	ds_read_b128 v[194:197], v190 offset:2048
	ds_read_b128 v[198:201], v190 offset:3072
	v_lshl_add_u64 v[190:191], s[64:65], 0, v[212:213]
	s_mov_b32 m0, s96
	v_lshl_add_u64 v[202:203], s[64:65], 0, v[164:165]
	global_load_lds_dwordx4 v[190:191], off
	s_add_i32 m0, s96, 0x2000
	s_nop 0
	global_load_lds_dwordx4 v[202:203], off
	s_barrier
	s_waitcnt lgkmcnt(0)
	s_setprio 1
	s_waitcnt lgkmcnt(0)
	v_mfma_f32_16x16x32_bf16 v[116:119], v[182:185], v[144:147], v[116:119]
	v_mfma_f32_16x16x32_bf16 v[112:115], v[194:197], v[144:147], v[112:115]
	v_mfma_f32_16x16x32_bf16 v[100:103], v[182:185], v[152:155], v[100:103]
	v_mfma_f32_16x16x32_bf16 v[96:99], v[194:197], v[152:155], v[96:99]
	v_mfma_f32_16x16x32_bf16 v[84:87], v[182:185], v[160:163], v[84:87]
	v_mfma_f32_16x16x32_bf16 v[80:83], v[194:197], v[160:163], v[80:83]
	v_mfma_f32_16x16x32_bf16 v[68:71], v[182:185], v[174:177], v[68:71]
	v_mfma_f32_16x16x32_bf16 v[64:67], v[194:197], v[174:177], v[64:67]
	v_mfma_f32_16x16x32_bf16 v[116:119], v[186:189], v[148:151], v[116:119]
	v_mfma_f32_16x16x32_bf16 v[112:115], v[198:201], v[148:151], v[112:115]
	v_mfma_f32_16x16x32_bf16 v[100:103], v[186:189], v[156:159], v[100:103]
	v_mfma_f32_16x16x32_bf16 v[96:99], v[198:201], v[156:159], v[96:99]
	v_mfma_f32_16x16x32_bf16 v[84:87], v[186:189], v[170:173], v[84:87]
	v_mfma_f32_16x16x32_bf16 v[80:83], v[198:201], v[170:173], v[80:83]
	v_mfma_f32_16x16x32_bf16 v[68:71], v[186:189], v[178:181], v[68:71]
	v_mfma_f32_16x16x32_bf16 v[64:67], v[198:201], v[178:181], v[64:67]
	s_setprio 0
	s_mov_b32 m0, s24
	v_lshl_add_u64 v[204:205], s[70:71], 0, v[212:213]
	s_barrier
	ds_read_b128 v[144:147], v193 offset:16384
	ds_read_b128 v[148:151], v193 offset:17408
	ds_read_b128 v[152:155], v193 offset:18432
	ds_read_b128 v[156:159], v193 offset:19456
	ds_read_b128 v[160:163], v193 offset:20480
	ds_read_b128 v[170:173], v193 offset:21504
	ds_read_b128 v[174:177], v193 offset:22528
	ds_read_b128 v[178:181], v193 offset:23552
	global_load_lds_dwordx4 v[204:205], off
	v_lshl_add_u64 v[206:207], s[70:71], 0, v[164:165]
	s_mov_b32 m0, s46
	s_nop 0
	global_load_lds_dwordx4 v[206:207], off
	s_barrier
	s_waitcnt lgkmcnt(0)
	s_setprio 1
	s_waitcnt lgkmcnt(0)
	v_mfma_f32_16x16x32_bf16 v[60:63], v[128:131], v[144:147], v[60:63]
	v_mfma_f32_16x16x32_bf16 v[56:59], v[136:139], v[144:147], v[56:59]
	v_mfma_f32_16x16x32_bf16 v[44:47], v[128:131], v[152:155], v[44:47]
	v_mfma_f32_16x16x32_bf16 v[40:43], v[136:139], v[152:155], v[40:43]
	v_mfma_f32_16x16x32_bf16 v[28:31], v[128:131], v[160:163], v[28:31]
	v_mfma_f32_16x16x32_bf16 v[24:27], v[136:139], v[160:163], v[24:27]
	v_mfma_f32_16x16x32_bf16 v[12:15], v[128:131], v[174:177], v[12:15]
	v_mfma_f32_16x16x32_bf16 v[8:11], v[136:139], v[174:177], v[8:11]
	v_mfma_f32_16x16x32_bf16 v[60:63], v[132:135], v[148:151], v[60:63]
	v_mfma_f32_16x16x32_bf16 v[56:59], v[140:143], v[148:151], v[56:59]
	v_mfma_f32_16x16x32_bf16 v[44:47], v[132:135], v[156:159], v[44:47]
	v_mfma_f32_16x16x32_bf16 v[40:43], v[140:143], v[156:159], v[40:43]
	v_mfma_f32_16x16x32_bf16 v[28:31], v[132:135], v[170:173], v[28:31]
	v_mfma_f32_16x16x32_bf16 v[24:27], v[140:143], v[170:173], v[24:27]
	v_mfma_f32_16x16x32_bf16 v[12:15], v[132:135], v[178:181], v[12:15]
	v_mfma_f32_16x16x32_bf16 v[8:11], v[140:143], v[178:181], v[8:11]
	s_setprio 0
	s_barrier
; #define PG8_STAGE(bufoff, gbase, voff) do { _Pragma("unroll") for (int _i = 0; _i < 2; ++_i) \
;         __builtin_amdgcn_global_load_lds((const unsigned*)((const char*)(gbase) + (voff)[_i]), (LAS unsigned*)(lds + (bufoff) + ldsw + _i * 8192), 16, 0, 0); } while (0)
; #define PG8_LDA(dst, b, h) do { _Pragma("unroll") for (int m = 0; m < 4; ++m) _Pragma("unroll") for (int k = 0; k < 2; ++k) dst[m][k] = *(const LAS bf16x8*)(lds + PG8_SA(b, h) + aoff + m * 2048 + k * 1024); } while (0)
; #define PG8_LDB(dst, b, h) do { _Pragma("unroll") for (int n = 0; n < 2; ++n) _Pragma("unroll") for (int k = 0; k < 2; ++k) dst[n][k] = *(const LAS bf16x8*)(lds + PG8_SB(b, h) + boff + n * 2048 + k * 1024); } while (0)
; #define PG8_MMA(ai, bj, At, Bt) do { __builtin_amdgcn_s_setprio(1); _Pragma("unroll") for (int m = 0; m < 4; ++m) _Pragma("unroll") for (int n = 0; n < 2; ++n) _Pragma("unroll") for (int k = 0; k < 2; ++k) \
;         acc[ai][bj][m][n] = __builtin_amdgcn_mfma_f32_16x16x32_bf16(Bt[n][k], At[m][k], acc[ai][bj][m][n], 0, 0, 0); __builtin_amdgcn_s_setprio(0); } while (0)
; #define PG8_WAIT_V(n) asm volatile("s_waitcnt vmcnt(" #n ")" ::: "memory")
; #define PG8_WAIT_L(n) asm volatile("s_waitcnt lgkmcnt(" #n ")" ::: "memory")
; #define PG8_BAR __builtin_amdgcn_s_barrier()
; #define PG8_SCHED __builtin_amdgcn_sched_barrier(0)
; template <class Epi>
; __device__ __forceinline__ void gemm_phase(LAS unsigned char* lds, const Gemm g, const StaticOrder& S, const Epi& E, int wv) {
;     ...
;             PG8_BAR; PG8_WAIT_L(0); PG8_MMA(1, 0, At, B0); PG8_BAR; PG8_SCHED;
;             PG8_STAGE(PG8_SB(0, 1), b2 + hstep, voffB);
;             PG8_WAIT_V(6); PG8_BAR; PG8_MMA(1, 1, At, B1); PG8_BAR;
;             PG8_LDB(B0, 1, 0); PG8_SCHED; PG8_LDA(At, 1, 0); PG8_STAGE(PG8_SA(0, 1), a2 + hstep, voffA);
;             PG8_WAIT_L(8); PG8_BAR; PG8_WAIT_L(0); PG8_MMA(0, 0, At, B0); PG8_BAR; PG8_SCHED;
;             PG8_LDB(B1, 1, 1); PG8_STAGE(PG8_SB(1, 0), b3, voffB);
;             PG8_BAR; PG8_WAIT_L(0); PG8_MMA(0, 1, At, B1); PG8_BAR;
;             PG8_LDA(At, 1, 1); PG8_STAGE(PG8_SA(1, 0), a3, voffA);
;             PG8_BAR; PG8_WAIT_L(0); PG8_MMA(1, 0, At, B0); PG8_BAR; PG8_SCHED;
	s_add_u32 s96, s64, 0x80000
	s_addc_u32 s97, s65, 0
	s_add_i32 vcc_lo, vcc_lo, s37
	v_lshl_add_u64 v[128:129], s[96:97], 0, v[212:213]
	s_mov_b32 m0, vcc_lo
	s_nop 0
	global_load_lds_dwordx4 v[128:129], off
	v_lshl_add_u64 v[128:129], s[96:97], 0, v[164:165]
	s_add_i32 m0, vcc_lo, 0x2000
	s_nop 0
	global_load_lds_dwordx4 v[128:129], off
	s_waitcnt vmcnt(6)
	s_barrier
	s_setprio 1
	v_mfma_f32_16x16x32_bf16 v[52:55], v[182:185], v[144:147], v[52:55]
	v_mfma_f32_16x16x32_bf16 v[48:51], v[194:197], v[144:147], v[48:51]
	v_mfma_f32_16x16x32_bf16 v[36:39], v[182:185], v[152:155], v[36:39]
	v_mfma_f32_16x16x32_bf16 v[32:35], v[194:197], v[152:155], v[32:35]
	v_mfma_f32_16x16x32_bf16 v[20:23], v[182:185], v[160:163], v[20:23]
	v_mfma_f32_16x16x32_bf16 v[16:19], v[194:197], v[160:163], v[16:19]
	v_mfma_f32_16x16x32_bf16 v[4:7], v[182:185], v[174:177], v[4:7]
	v_mfma_f32_16x16x32_bf16 v[0:3], v[194:197], v[174:177], v[0:3]
	v_mfma_f32_16x16x32_bf16 v[52:55], v[186:189], v[148:151], v[52:55]
	v_mfma_f32_16x16x32_bf16 v[48:51], v[198:201], v[148:151], v[48:51]
	v_mfma_f32_16x16x32_bf16 v[36:39], v[186:189], v[156:159], v[36:39]
	v_mfma_f32_16x16x32_bf16 v[32:35], v[198:201], v[156:159], v[32:35]
	v_mfma_f32_16x16x32_bf16 v[20:23], v[186:189], v[170:173], v[20:23]
	v_mfma_f32_16x16x32_bf16 v[16:19], v[198:201], v[170:173], v[16:19]
	v_mfma_f32_16x16x32_bf16 v[4:7], v[186:189], v[178:181], v[4:7]
	v_mfma_f32_16x16x32_bf16 v[0:3], v[198:201], v[178:181], v[0:3]
	s_setprio 0
	s_add_i32 s96, 0, 0x18000
	v_add_u32_e32 v140, s96, v192
	s_barrier
	ds_read_b128 v[128:131], v140
	ds_read_b128 v[132:135], v140 offset:1024
	ds_read_b128 v[136:139], v140 offset:2048
	ds_read_b128 v[140:143], v140 offset:3072
	s_add_u32 s70, s70, 0x80000
	s_addc_u32 s71, s71, 0
	s_mov_b32 m0, s47
	v_lshl_add_u64 v[182:183], s[70:71], 0, v[212:213]
	ds_read_b128 v[144:147], v193 offset:32768
	ds_read_b128 v[148:151], v193 offset:33792
	ds_read_b128 v[152:155], v193 offset:34816
	ds_read_b128 v[156:159], v193 offset:35840
	ds_read_b128 v[160:163], v193 offset:36864
	ds_read_b128 v[170:173], v193 offset:37888
	ds_read_b128 v[174:177], v193 offset:38912
	ds_read_b128 v[178:181], v193 offset:39936
	global_load_lds_dwordx4 v[182:183], off
	v_lshl_add_u64 v[182:183], s[70:71], 0, v[164:165]
	s_mov_b32 m0, s50
	s_nop 0
	global_load_lds_dwordx4 v[182:183], off
	s_waitcnt lgkmcnt(8)
	s_barrier
	s_waitcnt lgkmcnt(0)
	s_setprio 1
	s_waitcnt lgkmcnt(0)
	v_mfma_f32_16x16x32_bf16 v[124:127], v[128:131], v[144:147], v[124:127]
	v_mfma_f32_16x16x32_bf16 v[120:123], v[136:139], v[144:147], v[120:123]
	v_mfma_f32_16x16x32_bf16 v[108:111], v[128:131], v[152:155], v[108:111]
	v_mfma_f32_16x16x32_bf16 v[104:107], v[136:139], v[152:155], v[104:107]
	v_mfma_f32_16x16x32_bf16 v[92:95], v[128:131], v[160:163], v[92:95]
	v_mfma_f32_16x16x32_bf16 v[88:91], v[136:139], v[160:163], v[88:91]
	v_mfma_f32_16x16x32_bf16 v[76:79], v[128:131], v[174:177], v[76:79]
	v_mfma_f32_16x16x32_bf16 v[72:75], v[136:139], v[174:177], v[72:75]
	v_mfma_f32_16x16x32_bf16 v[124:127], v[132:135], v[148:151], v[124:127]
	v_mfma_f32_16x16x32_bf16 v[120:123], v[140:143], v[148:151], v[120:123]
	v_mfma_f32_16x16x32_bf16 v[108:111], v[132:135], v[156:159], v[108:111]
	v_mfma_f32_16x16x32_bf16 v[104:107], v[140:143], v[156:159], v[104:107]
	v_mfma_f32_16x16x32_bf16 v[92:95], v[132:135], v[170:173], v[92:95]
	v_mfma_f32_16x16x32_bf16 v[88:91], v[140:143], v[170:173], v[88:91]
	v_mfma_f32_16x16x32_bf16 v[76:79], v[132:135], v[178:181], v[76:79]
	v_mfma_f32_16x16x32_bf16 v[72:75], v[140:143], v[178:181], v[72:75]
	s_setprio 0
	s_barrier
	s_add_i32 s70, 0, 0x1c000
	s_add_i32 s71, s96, s37
	v_add_u32_e32 v198, s70, v192
	v_lshl_add_u64 v[190:191], v[190:191], 0, s[80:81]
	s_mov_b32 m0, s71
	ds_read_b128 v[182:185], v198
	ds_read_b128 v[186:189], v198 offset:1024
	ds_read_b128 v[194:197], v198 offset:2048
	ds_read_b128 v[198:201], v198 offset:3072
	global_load_lds_dwordx4 v[190:191], off
	v_lshl_add_u64 v[190:191], v[202:203], 0, s[80:81]
	s_add_i32 m0, s71, 0x2000
	s_nop 0
	global_load_lds_dwordx4 v[190:191], off
	s_barrier
	s_waitcnt lgkmcnt(0)
	s_setprio 1
	s_waitcnt lgkmcnt(0)
	v_mfma_f32_16x16x32_bf16 v[116:119], v[182:185], v[144:147], v[116:119]
	v_mfma_f32_16x16x32_bf16 v[112:115], v[194:197], v[144:147], v[112:115]
	v_mfma_f32_16x16x32_bf16 v[100:103], v[182:185], v[152:155], v[100:103]
	v_mfma_f32_16x16x32_bf16 v[96:99], v[194:197], v[152:155], v[96:99]
	v_mfma_f32_16x16x32_bf16 v[84:87], v[182:185], v[160:163], v[84:87]
	v_mfma_f32_16x16x32_bf16 v[80:83], v[194:197], v[160:163], v[80:83]
	v_mfma_f32_16x16x32_bf16 v[68:71], v[182:185], v[174:177], v[68:71]
	v_mfma_f32_16x16x32_bf16 v[64:67], v[194:197], v[174:177], v[64:67]
	v_mfma_f32_16x16x32_bf16 v[116:119], v[186:189], v[148:151], v[116:119]
	v_mfma_f32_16x16x32_bf16 v[112:115], v[198:201], v[148:151], v[112:115]
	v_mfma_f32_16x16x32_bf16 v[100:103], v[186:189], v[156:159], v[100:103]
	v_mfma_f32_16x16x32_bf16 v[96:99], v[198:201], v[156:159], v[96:99]
	v_mfma_f32_16x16x32_bf16 v[84:87], v[186:189], v[170:173], v[84:87]
	v_mfma_f32_16x16x32_bf16 v[80:83], v[198:201], v[170:173], v[80:83]
	v_mfma_f32_16x16x32_bf16 v[68:71], v[186:189], v[178:181], v[68:71]
	v_mfma_f32_16x16x32_bf16 v[64:67], v[198:201], v[178:181], v[64:67]
	s_setprio 0
	s_mov_b32 m0, s72
	v_lshl_add_u64 v[190:191], v[204:205], 0, s[80:81]
	s_barrier
	ds_read_b128 v[144:147], v193 offset:49152
	ds_read_b128 v[148:151], v193 offset:50176
	ds_read_b128 v[152:155], v193 offset:51200
	ds_read_b128 v[156:159], v193 offset:52224
	ds_read_b128 v[160:163], v193 offset:53248
	ds_read_b128 v[170:173], v193 offset:54272
	ds_read_b128 v[174:177], v193 offset:55296
	ds_read_b128 v[178:181], v193 offset:56320
	global_load_lds_dwordx4 v[190:191], off
	v_lshl_add_u64 v[190:191], v[206:207], 0, s[80:81]
	s_mov_b32 m0, s73
	s_nop 0
	global_load_lds_dwordx4 v[190:191], off
	s_barrier
; #define PG8_STAGE(bufoff, gbase, voff) do { _Pragma("unroll") for (int _i = 0; _i < 2; ++_i) \
;         __builtin_amdgcn_global_load_lds((const unsigned*)((const char*)(gbase) + (voff)[_i]), (LAS unsigned*)(lds + (bufoff) + ldsw + _i * 8192), 16, 0, 0); } while (0)
; #define PG8_MMA(ai, bj, At, Bt) do { __builtin_amdgcn_s_setprio(1); _Pragma("unroll") for (int m = 0; m < 4; ++m) _Pragma("unroll") for (int n = 0; n < 2; ++n) _Pragma("unroll") for (int k = 0; k < 2; ++k) \
;         acc[ai][bj][m][n] = __builtin_amdgcn_mfma_f32_16x16x32_bf16(Bt[n][k], At[m][k], acc[ai][bj][m][n], 0, 0, 0); __builtin_amdgcn_s_setprio(0); } while (0)
; #define PG8_WAIT_V(n) asm volatile("s_waitcnt vmcnt(" #n ")" ::: "memory")
; #define PG8_BAR __builtin_amdgcn_s_barrier()
; template <class Epi>
; __device__ __forceinline__ void gemm_phase(LAS unsigned char* lds, const Gemm g, const StaticOrder& S, const Epi& E, int wv) {
;     ...
;             PG8_BAR; PG8_WAIT_L(0); PG8_MMA(1, 0, At, B0); PG8_BAR; PG8_SCHED;
;             PG8_STAGE(PG8_SB(1, 1), b3 + hstep, voffB);
;             PG8_WAIT_V(6); PG8_BAR; PG8_MMA(1, 1, At, B1); PG8_BAR;
;     __device__ __forceinline__ void operator()(const Acc& acc, const Unit& u, int wv) const {
;     ...
;         const int row0 = u.pm * BM + wr * 64 + fr, col0 = u.pn * BM + wc * 32 + 4 * fq;
; #pragma unroll
;         for (int pr = 0; pr < 4; ++pr) {
;             f32x4 xi[2][4]; f32x2 st[2];
; #pragma unroll
;             for (int q = 0; q < 2; ++q) { const int i = pr * 2 + q, row = row0 + (i >> 2) * HALF + (i & 3) * 16; const size_t ro = (size_t)row * 1024 + col0;
;                 st[q] = (f32x2){0.f, 1.f}; if (ST) st[q] = ST[row];
; #pragma unroll
;                 for (int c4 = 0; c4 < 4; ++c4) xi[q][c4] = *(const f32x4*)(XIN + ro + (c4 >> 1) * HALF + (c4 & 1) * 16); }
; #pragma unroll
;             for (int q = 0; q < 2; ++q) { const int i = pr * 2 + q, row = row0 + (i >> 2) * HALF + (i & 3) * 16; const size_t ro = (size_t)row * 1024 + col0;
; #pragma unroll
;                 for (int c4 = 0; c4 < 4; ++c4) { const int co = (c4 >> 1) * HALF + (c4 & 1) * 16; f32x4 x = xi[q][c4];
;                     if (ST) { const f32x4 g = *(const f32x4*)(G + col0 + co), b = *(const f32x4*)(B + col0 + co); x = (x - st[q][0]) * st[q][1] * g + b; }
;                     if (!nowrite) *(f32x4*)(XRES + ro + co) = acc[i >> 2][c4 >> 1][i & 3][c4 & 1] + x * ALPHA; } }
	s_waitcnt lgkmcnt(0)
	s_setprio 1
	s_waitcnt lgkmcnt(0)
	v_mfma_f32_16x16x32_bf16 v[60:63], v[128:131], v[144:147], v[60:63]
	v_mfma_f32_16x16x32_bf16 v[56:59], v[136:139], v[144:147], v[56:59]
	v_mfma_f32_16x16x32_bf16 v[44:47], v[128:131], v[152:155], v[44:47]
	v_mfma_f32_16x16x32_bf16 v[40:43], v[136:139], v[152:155], v[40:43]
	v_mfma_f32_16x16x32_bf16 v[28:31], v[128:131], v[160:163], v[28:31]
	v_mfma_f32_16x16x32_bf16 v[24:27], v[136:139], v[160:163], v[24:27]
	v_mfma_f32_16x16x32_bf16 v[12:15], v[128:131], v[174:177], v[12:15]
	v_mfma_f32_16x16x32_bf16 v[8:11], v[136:139], v[174:177], v[8:11]
	v_mfma_f32_16x16x32_bf16 v[60:63], v[132:135], v[148:151], v[60:63]
	v_mfma_f32_16x16x32_bf16 v[56:59], v[140:143], v[148:151], v[56:59]
	v_mfma_f32_16x16x32_bf16 v[44:47], v[132:135], v[156:159], v[44:47]
	v_mfma_f32_16x16x32_bf16 v[40:43], v[140:143], v[156:159], v[40:43]
	v_mfma_f32_16x16x32_bf16 v[28:31], v[132:135], v[170:173], v[28:31]
	v_mfma_f32_16x16x32_bf16 v[24:27], v[140:143], v[170:173], v[24:27]
	v_mfma_f32_16x16x32_bf16 v[12:15], v[132:135], v[178:181], v[12:15]
	v_mfma_f32_16x16x32_bf16 v[8:11], v[140:143], v[178:181], v[8:11]
	s_setprio 0
	s_barrier
	s_add_u32 s64, s64, 0x80080
	s_addc_u32 s65, s65, 0
	s_add_i32 s70, s70, s37
	v_lshl_add_u64 v[128:129], s[64:65], 0, v[212:213]
	s_mov_b32 m0, s70
	s_nop 0
	global_load_lds_dwordx4 v[128:129], off
	v_lshl_add_u64 v[128:129], s[64:65], 0, v[164:165]
	s_add_i32 m0, s70, 0x2000
	s_nop 0
	global_load_lds_dwordx4 v[128:129], off
	s_waitcnt vmcnt(6)
	s_barrier
	s_setprio 1
	v_mfma_f32_16x16x32_bf16 v[52:55], v[182:185], v[144:147], v[52:55]
	v_mfma_f32_16x16x32_bf16 v[48:51], v[194:197], v[144:147], v[48:51]
	v_mfma_f32_16x16x32_bf16 v[36:39], v[182:185], v[152:155], v[36:39]
	v_mfma_f32_16x16x32_bf16 v[32:35], v[194:197], v[152:155], v[32:35]
	v_mfma_f32_16x16x32_bf16 v[20:23], v[182:185], v[160:163], v[20:23]
	v_mfma_f32_16x16x32_bf16 v[16:19], v[194:197], v[160:163], v[16:19]
	v_mfma_f32_16x16x32_bf16 v[4:7], v[182:185], v[174:177], v[4:7]
	v_mfma_f32_16x16x32_bf16 v[0:3], v[194:197], v[174:177], v[0:3]
	v_mfma_f32_16x16x32_bf16 v[52:55], v[186:189], v[148:151], v[52:55]
	v_mfma_f32_16x16x32_bf16 v[48:51], v[198:201], v[148:151], v[48:51]
	v_mfma_f32_16x16x32_bf16 v[36:39], v[186:189], v[156:159], v[36:39]
	v_mfma_f32_16x16x32_bf16 v[32:35], v[198:201], v[156:159], v[32:35]
	v_mfma_f32_16x16x32_bf16 v[20:23], v[186:189], v[170:173], v[20:23]
	v_mfma_f32_16x16x32_bf16 v[16:19], v[198:201], v[170:173], v[16:19]
	v_mfma_f32_16x16x32_bf16 v[4:7], v[186:189], v[178:181], v[4:7]
	v_mfma_f32_16x16x32_bf16 v[0:3], v[198:201], v[178:181], v[0:3]
	s_setprio 0
	s_add_i32 s86, s86, 2
	s_add_u32 s8, s8, 0x100
	s_addc_u32 s9, s9, 0
	s_add_u32 s79, s79, 0x100
	s_addc_u32 s85, s85, 0
	s_cmp_gt_u32 s86, 29
	s_barrier
	s_cbranch_scc0 .LBB0_424
	s_lshl_b32 s8, s78, 8
	v_readlane_b32 s9, v254, 13
	v_mov_b32_e32 v186, v233
	s_lshl_b32 s34, s77, 8
	s_add_i32 s8, s8, s9
	s_or_b32 s34, s34, s53
	v_and_or_b32 v187, v186, 15, s8
	v_ashrrev_i32_e32 v188, 2, v186
	v_and_b32_e32 v188, -4, v188
	v_add_u32_e32 v188, s34, v188
	v_lshlrev_b32_e32 v188, 2, v188
	v_lshl_add_u32 v186, v187, 12, v188
	v_lshlrev_b32_e32 v187, 3, v187
	s_movk_i32 s85, 0x1800
	v_readlane_b32 s79, v255, 14
	v_readlane_b32 s96, v255, 9
	s_andn2_b64 vcc, exec, s[20:21]
	s_cbranch_vccnz .Lepi_res_nost
	global_load_dwordx4 v[160:163], v188, s[10:11]
	global_load_dwordx4 v[170:173], v188, s[10:11] offset:64
	global_load_dwordx4 v[174:177], v188, s[10:11] offset:512
	global_load_dwordx4 v[178:181], v188, s[10:11] offset:576
	global_load_dwordx4 v[128:131], v188, s[56:57]
	global_load_dwordx4 v[132:135], v188, s[56:57] offset:64
	global_load_dwordx4 v[136:139], v188, s[56:57] offset:512
	global_load_dwordx4 v[140:143], v188, s[56:57] offset:576
	global_load_dwordx2 v[182:183], v187, s[42:43]
	global_load_dwordx4 v[144:147], v186, s[22:23]
	global_load_dwordx4 v[148:151], v186, s[22:23] offset:64
	global_load_dwordx4 v[152:155], v186, s[22:23] offset:512
	global_load_dwordx4 v[156:159], v186, s[22:23] offset:576
	s_waitcnt vmcnt(9)
	v_pk_fma_f32 v[124:125], v[160:161], s[28:29], v[124:125] op_sel_hi:[1,0,1]
	v_pk_fma_f32 v[126:127], v[162:163], s[28:29], v[126:127] op_sel_hi:[1,0,1]
	v_pk_fma_f32 v[120:121], v[170:171], s[28:29], v[120:121] op_sel_hi:[1,0,1]
	v_pk_fma_f32 v[122:123], v[172:173], s[28:29], v[122:123] op_sel_hi:[1,0,1]
	v_pk_fma_f32 v[116:117], v[174:175], s[28:29], v[116:117] op_sel_hi:[1,0,1]
	v_pk_fma_f32 v[118:119], v[176:177], s[28:29], v[118:119] op_sel_hi:[1,0,1]
	v_pk_fma_f32 v[112:113], v[178:179], s[28:29], v[112:113] op_sel_hi:[1,0,1]
	v_pk_fma_f32 v[114:115], v[180:181], s[28:29], v[114:115] op_sel_hi:[1,0,1]
	v_pk_fma_f32 v[108:109], v[160:161], s[28:29], v[108:109] op_sel_hi:[1,0,1]
	v_pk_fma_f32 v[110:111], v[162:163], s[28:29], v[110:111] op_sel_hi:[1,0,1]
	v_pk_fma_f32 v[104:105], v[170:171], s[28:29], v[104:105] op_sel_hi:[1,0,1]
	v_pk_fma_f32 v[106:107], v[172:173], s[28:29], v[106:107] op_sel_hi:[1,0,1]
	v_pk_fma_f32 v[100:101], v[174:175], s[28:29], v[100:101] op_sel_hi:[1,0,1]
	v_pk_fma_f32 v[102:103], v[176:177], s[28:29], v[102:103] op_sel_hi:[1,0,1]
	v_pk_fma_f32 v[96:97], v[178:179], s[28:29], v[96:97] op_sel_hi:[1,0,1]
	v_pk_fma_f32 v[98:99], v[180:181], s[28:29], v[98:99] op_sel_hi:[1,0,1]
	v_pk_fma_f32 v[92:93], v[160:161], s[28:29], v[92:93] op_sel_hi:[1,0,1]
	v_pk_fma_f32 v[94:95], v[162:163], s[28:29], v[94:95] op_sel_hi:[1,0,1]
	v_pk_fma_f32 v[88:89], v[170:171], s[28:29], v[88:89] op_sel_hi:[1,0,1]
	v_pk_fma_f32 v[90:91], v[172:173], s[28:29], v[90:91] op_sel_hi:[1,0,1]
;     __device__ __forceinline__ void operator()(const Acc& acc, const Unit& u, int wv) const {
;     ...
;             for (int q = 0; q < 2; ++q) { const int i = pr * 2 + q, row = row0 + (i >> 2) * HALF + (i & 3) * 16; const size_t ro = (size_t)row * 1024 + col0;
;                 st[q] = (f32x2){0.f, 1.f}; if (ST) st[q] = ST[row];
; #pragma unroll
;                 for (int c4 = 0; c4 < 4; ++c4) xi[q][c4] = *(const f32x4*)(XIN + ro + (c4 >> 1) * HALF + (c4 & 1) * 16); }
; #pragma unroll
;             for (int q = 0; q < 2; ++q) { const int i = pr * 2 + q, row = row0 + (i >> 2) * HALF + (i & 3) * 16; const size_t ro = (size_t)row * 1024 + col0;
; #pragma unroll
;                 for (int c4 = 0; c4 < 4; ++c4) { const int co = (c4 >> 1) * HALF + (c4 & 1) * 16; f32x4 x = xi[q][c4];
;                     if (ST) { const f32x4 g = *(const f32x4*)(G + col0 + co), b = *(const f32x4*)(B + col0 + co); x = (x - st[q][0]) * st[q][1] * g + b; }
;                     if (!nowrite) *(f32x4*)(XRES + ro + co) = acc[i >> 2][c4 >> 1][i & 3][c4 & 1] + x * ALPHA; } }
	v_pk_fma_f32 v[84:85], v[174:175], s[28:29], v[84:85] op_sel_hi:[1,0,1]
	v_pk_fma_f32 v[86:87], v[176:177], s[28:29], v[86:87] op_sel_hi:[1,0,1]
	v_pk_fma_f32 v[80:81], v[178:179], s[28:29], v[80:81] op_sel_hi:[1,0,1]
	v_pk_fma_f32 v[82:83], v[180:181], s[28:29], v[82:83] op_sel_hi:[1,0,1]
	v_pk_fma_f32 v[76:77], v[160:161], s[28:29], v[76:77] op_sel_hi:[1,0,1]
	v_pk_fma_f32 v[78:79], v[162:163], s[28:29], v[78:79] op_sel_hi:[1,0,1]
	v_pk_fma_f32 v[72:73], v[170:171], s[28:29], v[72:73] op_sel_hi:[1,0,1]
	v_pk_fma_f32 v[74:75], v[172:173], s[28:29], v[74:75] op_sel_hi:[1,0,1]
	v_pk_fma_f32 v[68:69], v[174:175], s[28:29], v[68:69] op_sel_hi:[1,0,1]
	v_pk_fma_f32 v[70:71], v[176:177], s[28:29], v[70:71] op_sel_hi:[1,0,1]
	v_pk_fma_f32 v[64:65], v[178:179], s[28:29], v[64:65] op_sel_hi:[1,0,1]
	v_pk_fma_f32 v[66:67], v[180:181], s[28:29], v[66:67] op_sel_hi:[1,0,1]
	v_pk_fma_f32 v[60:61], v[160:161], s[28:29], v[60:61] op_sel_hi:[1,0,1]
	v_pk_fma_f32 v[62:63], v[162:163], s[28:29], v[62:63] op_sel_hi:[1,0,1]
	v_pk_fma_f32 v[56:57], v[170:171], s[28:29], v[56:57] op_sel_hi:[1,0,1]
	v_pk_fma_f32 v[58:59], v[172:173], s[28:29], v[58:59] op_sel_hi:[1,0,1]
	v_pk_fma_f32 v[52:53], v[174:175], s[28:29], v[52:53] op_sel_hi:[1,0,1]
	v_pk_fma_f32 v[54:55], v[176:177], s[28:29], v[54:55] op_sel_hi:[1,0,1]
	v_pk_fma_f32 v[48:49], v[178:179], s[28:29], v[48:49] op_sel_hi:[1,0,1]
	v_pk_fma_f32 v[50:51], v[180:181], s[28:29], v[50:51] op_sel_hi:[1,0,1]
	v_pk_fma_f32 v[44:45], v[160:161], s[28:29], v[44:45] op_sel_hi:[1,0,1]
	v_pk_fma_f32 v[46:47], v[162:163], s[28:29], v[46:47] op_sel_hi:[1,0,1]
	v_pk_fma_f32 v[40:41], v[170:171], s[28:29], v[40:41] op_sel_hi:[1,0,1]
	v_pk_fma_f32 v[42:43], v[172:173], s[28:29], v[42:43] op_sel_hi:[1,0,1]
	v_pk_fma_f32 v[36:37], v[174:175], s[28:29], v[36:37] op_sel_hi:[1,0,1]
	v_pk_fma_f32 v[38:39], v[176:177], s[28:29], v[38:39] op_sel_hi:[1,0,1]
	v_pk_fma_f32 v[32:33], v[178:179], s[28:29], v[32:33] op_sel_hi:[1,0,1]
	v_pk_fma_f32 v[34:35], v[180:181], s[28:29], v[34:35] op_sel_hi:[1,0,1]
	v_pk_fma_f32 v[28:29], v[160:161], s[28:29], v[28:29] op_sel_hi:[1,0,1]
	v_pk_fma_f32 v[30:31], v[162:163], s[28:29], v[30:31] op_sel_hi:[1,0,1]
	v_pk_fma_f32 v[24:25], v[170:171], s[28:29], v[24:25] op_sel_hi:[1,0,1]
	v_pk_fma_f32 v[26:27], v[172:173], s[28:29], v[26:27] op_sel_hi:[1,0,1]
	v_pk_fma_f32 v[20:21], v[174:175], s[28:29], v[20:21] op_sel_hi:[1,0,1]
	v_pk_fma_f32 v[22:23], v[176:177], s[28:29], v[22:23] op_sel_hi:[1,0,1]
	v_pk_fma_f32 v[16:17], v[178:179], s[28:29], v[16:17] op_sel_hi:[1,0,1]
	v_pk_fma_f32 v[18:19], v[180:181], s[28:29], v[18:19] op_sel_hi:[1,0,1]
	v_pk_fma_f32 v[12:13], v[160:161], s[28:29], v[12:13] op_sel_hi:[1,0,1]
	v_pk_fma_f32 v[14:15], v[162:163], s[28:29], v[14:15] op_sel_hi:[1,0,1]
	v_pk_fma_f32 v[8:9], v[170:171], s[28:29], v[8:9] op_sel_hi:[1,0,1]
	v_pk_fma_f32 v[10:11], v[172:173], s[28:29], v[10:11] op_sel_hi:[1,0,1]
	v_pk_fma_f32 v[4:5], v[174:175], s[28:29], v[4:5] op_sel_hi:[1,0,1]
	v_pk_fma_f32 v[6:7], v[176:177], s[28:29], v[6:7] op_sel_hi:[1,0,1]
	v_pk_fma_f32 v[0:1], v[178:179], s[28:29], v[0:1] op_sel_hi:[1,0,1]
	v_pk_fma_f32 v[2:3], v[180:181], s[28:29], v[2:3] op_sel_hi:[1,0,1]
	v_add_u32_e32 v189, 0x10000, v186
	global_load_dwordx2 v[184:185], v187, s[42:43] offset:128
	global_load_dwordx4 v[160:163], v189, s[22:23]
	global_load_dwordx4 v[170:173], v189, s[22:23] offset:64
	global_load_dwordx4 v[174:177], v189, s[22:23] offset:512
	global_load_dwordx4 v[178:181], v189, s[22:23] offset:576
	s_waitcnt vmcnt(5)
	v_mov_b32_e32 v194, v183
	v_mov_b32_e32 v195, v183
	v_sub_f32_e32 v144, v144, v182
	v_sub_f32_e32 v145, v145, v182
	v_sub_f32_e32 v146, v146, v182
	v_sub_f32_e32 v147, v147, v182
	v_pk_mul_f32 v[144:145], v[194:195], v[144:145]
	v_pk_mul_f32 v[146:147], v[194:195], v[146:147]
	v_pk_mul_f32 v[144:145], v[144:145], v[128:129]
	v_pk_mul_f32 v[146:147], v[146:147], v[130:131]
	v_pk_fma_f32 v[124:125], v[144:145], s[28:29], v[124:125] op_sel_hi:[1,0,1]
	v_pk_fma_f32 v[126:127], v[146:147], s[28:29], v[126:127] op_sel_hi:[1,0,1]
	v_sub_f32_e32 v148, v148, v182
	v_sub_f32_e32 v149, v149, v182
	v_sub_f32_e32 v150, v150, v182
	v_sub_f32_e32 v151, v151, v182
	v_pk_mul_f32 v[148:149], v[194:195], v[148:149]
	v_pk_mul_f32 v[150:151], v[194:195], v[150:151]
	v_pk_mul_f32 v[148:149], v[148:149], v[132:133]
	v_pk_mul_f32 v[150:151], v[150:151], v[134:135]
	v_pk_fma_f32 v[120:121], v[148:149], s[28:29], v[120:121] op_sel_hi:[1,0,1]
	v_pk_fma_f32 v[122:123], v[150:151], s[28:29], v[122:123] op_sel_hi:[1,0,1]
	v_sub_f32_e32 v152, v152, v182
	v_sub_f32_e32 v153, v153, v182
	v_sub_f32_e32 v154, v154, v182
	v_sub_f32_e32 v155, v155, v182
	v_pk_mul_f32 v[152:153], v[194:195], v[152:153]
	v_pk_mul_f32 v[154:155], v[194:195], v[154:155]
	v_pk_mul_f32 v[152:153], v[152:153], v[136:137]
	v_pk_mul_f32 v[154:155], v[154:155], v[138:139]
	v_pk_fma_f32 v[116:117], v[152:153], s[28:29], v[116:117] op_sel_hi:[1,0,1]
	v_pk_fma_f32 v[118:119], v[154:155], s[28:29], v[118:119] op_sel_hi:[1,0,1]
	v_sub_f32_e32 v156, v156, v182
	v_sub_f32_e32 v157, v157, v182
	v_sub_f32_e32 v158, v158, v182
	v_sub_f32_e32 v159, v159, v182
	v_pk_mul_f32 v[156:157], v[194:195], v[156:157]
	v_pk_mul_f32 v[158:159], v[194:195], v[158:159]
	v_pk_mul_f32 v[156:157], v[156:157], v[140:141]
	v_pk_mul_f32 v[158:159], v[158:159], v[142:143]
	v_pk_fma_f32 v[112:113], v[156:157], s[28:29], v[112:113] op_sel_hi:[1,0,1]
	v_pk_fma_f32 v[114:115], v[158:159], s[28:29], v[114:115] op_sel_hi:[1,0,1]
	v_add_u32_e32 v189, 0x20000, v186
	global_load_dwordx2 v[182:183], v187, s[42:43] offset:256
	global_load_dwordx4 v[144:147], v189, s[22:23]
	global_load_dwordx4 v[148:151], v189, s[22:23] offset:64
	global_load_dwordx4 v[152:155], v189, s[22:23] offset:512
	global_load_dwordx4 v[156:159], v189, s[22:23] offset:576
	global_store_dwordx4 v186, v[124:127], s[18:19]
	global_store_dwordx4 v186, v[120:123], s[18:19] offset:64
	global_store_dwordx4 v186, v[116:119], s[18:19] offset:512
	global_store_dwordx4 v186, v[112:115], s[18:19] offset:576
	s_waitcnt vmcnt(9)
;     __device__ __forceinline__ void operator()(const Acc& acc, const Unit& u, int wv) const {
;     ...
;             for (int q = 0; q < 2; ++q) { const int i = pr * 2 + q, row = row0 + (i >> 2) * HALF + (i & 3) * 16; const size_t ro = (size_t)row * 1024 + col0;
;                 st[q] = (f32x2){0.f, 1.f}; if (ST) st[q] = ST[row];
; #pragma unroll
;                 for (int c4 = 0; c4 < 4; ++c4) xi[q][c4] = *(const f32x4*)(XIN + ro + (c4 >> 1) * HALF + (c4 & 1) * 16); }
; #pragma unroll
;             for (int q = 0; q < 2; ++q) { const int i = pr * 2 + q, row = row0 + (i >> 2) * HALF + (i & 3) * 16; const size_t ro = (size_t)row * 1024 + col0;
; #pragma unroll
;                 for (int c4 = 0; c4 < 4; ++c4) { const int co = (c4 >> 1) * HALF + (c4 & 1) * 16; f32x4 x = xi[q][c4];
;                     if (ST) { const f32x4 g = *(const f32x4*)(G + col0 + co), b = *(const f32x4*)(B + col0 + co); x = (x - st[q][0]) * st[q][1] * g + b; }
;                     if (!nowrite) *(f32x4*)(XRES + ro + co) = acc[i >> 2][c4 >> 1][i & 3][c4 & 1] + x * ALPHA; } }
	v_mov_b32_e32 v194, v185
	v_mov_b32_e32 v195, v185
	v_sub_f32_e32 v160, v160, v184
	v_sub_f32_e32 v161, v161, v184
	v_sub_f32_e32 v162, v162, v184
	v_sub_f32_e32 v163, v163, v184
	v_pk_mul_f32 v[160:161], v[194:195], v[160:161]
	v_pk_mul_f32 v[162:163], v[194:195], v[162:163]
	v_pk_mul_f32 v[160:161], v[160:161], v[128:129]
	v_pk_mul_f32 v[162:163], v[162:163], v[130:131]
	v_pk_fma_f32 v[108:109], v[160:161], s[28:29], v[108:109] op_sel_hi:[1,0,1]
	v_pk_fma_f32 v[110:111], v[162:163], s[28:29], v[110:111] op_sel_hi:[1,0,1]
	v_sub_f32_e32 v170, v170, v184
	v_sub_f32_e32 v171, v171, v184
	v_sub_f32_e32 v172, v172, v184
	v_sub_f32_e32 v173, v173, v184
	v_pk_mul_f32 v[170:171], v[194:195], v[170:171]
	v_pk_mul_f32 v[172:173], v[194:195], v[172:173]
	v_pk_mul_f32 v[170:171], v[170:171], v[132:133]
	v_pk_mul_f32 v[172:173], v[172:173], v[134:135]
	v_pk_fma_f32 v[104:105], v[170:171], s[28:29], v[104:105] op_sel_hi:[1,0,1]
	v_pk_fma_f32 v[106:107], v[172:173], s[28:29], v[106:107] op_sel_hi:[1,0,1]
	v_sub_f32_e32 v174, v174, v184
	v_sub_f32_e32 v175, v175, v184
	v_sub_f32_e32 v176, v176, v184
	v_sub_f32_e32 v177, v177, v184
	v_pk_mul_f32 v[174:175], v[194:195], v[174:175]
	v_pk_mul_f32 v[176:177], v[194:195], v[176:177]
	v_pk_mul_f32 v[174:175], v[174:175], v[136:137]
	v_pk_mul_f32 v[176:177], v[176:177], v[138:139]
	v_pk_fma_f32 v[100:101], v[174:175], s[28:29], v[100:101] op_sel_hi:[1,0,1]
	v_pk_fma_f32 v[102:103], v[176:177], s[28:29], v[102:103] op_sel_hi:[1,0,1]
	v_sub_f32_e32 v178, v178, v184
	v_sub_f32_e32 v179, v179, v184
	v_sub_f32_e32 v180, v180, v184
	v_sub_f32_e32 v181, v181, v184
	v_pk_mul_f32 v[178:179], v[194:195], v[178:179]
	v_pk_mul_f32 v[180:181], v[194:195], v[180:181]
	v_pk_mul_f32 v[178:179], v[178:179], v[140:141]
	v_pk_mul_f32 v[180:181], v[180:181], v[142:143]
	v_pk_fma_f32 v[96:97], v[178:179], s[28:29], v[96:97] op_sel_hi:[1,0,1]
	v_pk_fma_f32 v[98:99], v[180:181], s[28:29], v[98:99] op_sel_hi:[1,0,1]
	v_add_u32_e32 v189, 0x30000, v186
	global_load_dwordx2 v[184:185], v187, s[42:43] offset:384
	global_load_dwordx4 v[160:163], v189, s[22:23]
	global_load_dwordx4 v[170:173], v189, s[22:23] offset:64
	global_load_dwordx4 v[174:177], v189, s[22:23] offset:512
	global_load_dwordx4 v[178:181], v189, s[22:23] offset:576
	v_add_u32_e32 v190, 0x10000, v186
	global_store_dwordx4 v190, v[108:111], s[18:19]
	global_store_dwordx4 v190, v[104:107], s[18:19] offset:64
	global_store_dwordx4 v190, v[100:103], s[18:19] offset:512
	global_store_dwordx4 v190, v[96:99], s[18:19] offset:576
	s_waitcnt vmcnt(13)
	v_mov_b32_e32 v194, v183
	v_mov_b32_e32 v195, v183
	v_sub_f32_e32 v144, v144, v182
	v_sub_f32_e32 v145, v145, v182
	v_sub_f32_e32 v146, v146, v182
	v_sub_f32_e32 v147, v147, v182
	v_pk_mul_f32 v[144:145], v[194:195], v[144:145]
	v_pk_mul_f32 v[146:147], v[194:195], v[146:147]
	v_pk_mul_f32 v[144:145], v[144:145], v[128:129]
	v_pk_mul_f32 v[146:147], v[146:147], v[130:131]
	v_pk_fma_f32 v[92:93], v[144:145], s[28:29], v[92:93] op_sel_hi:[1,0,1]
	v_pk_fma_f32 v[94:95], v[146:147], s[28:29], v[94:95] op_sel_hi:[1,0,1]
	v_sub_f32_e32 v148, v148, v182
	v_sub_f32_e32 v149, v149, v182
	v_sub_f32_e32 v150, v150, v182
	v_sub_f32_e32 v151, v151, v182
	v_pk_mul_f32 v[148:149], v[194:195], v[148:149]
	v_pk_mul_f32 v[150:151], v[194:195], v[150:151]
	v_pk_mul_f32 v[148:149], v[148:149], v[132:133]
	v_pk_mul_f32 v[150:151], v[150:151], v[134:135]
	v_pk_fma_f32 v[88:89], v[148:149], s[28:29], v[88:89] op_sel_hi:[1,0,1]
	v_pk_fma_f32 v[90:91], v[150:151], s[28:29], v[90:91] op_sel_hi:[1,0,1]
	v_sub_f32_e32 v152, v152, v182
	v_sub_f32_e32 v153, v153, v182
	v_sub_f32_e32 v154, v154, v182
	v_sub_f32_e32 v155, v155, v182
	v_pk_mul_f32 v[152:153], v[194:195], v[152:153]
	v_pk_mul_f32 v[154:155], v[194:195], v[154:155]
	v_pk_mul_f32 v[152:153], v[152:153], v[136:137]
	v_pk_mul_f32 v[154:155], v[154:155], v[138:139]
	v_pk_fma_f32 v[84:85], v[152:153], s[28:29], v[84:85] op_sel_hi:[1,0,1]
	v_pk_fma_f32 v[86:87], v[154:155], s[28:29], v[86:87] op_sel_hi:[1,0,1]
	v_sub_f32_e32 v156, v156, v182
	v_sub_f32_e32 v157, v157, v182
	v_sub_f32_e32 v158, v158, v182
	v_sub_f32_e32 v159, v159, v182
	v_pk_mul_f32 v[156:157], v[194:195], v[156:157]
	v_pk_mul_f32 v[158:159], v[194:195], v[158:159]
	v_pk_mul_f32 v[156:157], v[156:157], v[140:141]
	v_pk_mul_f32 v[158:159], v[158:159], v[142:143]
	v_pk_fma_f32 v[80:81], v[156:157], s[28:29], v[80:81] op_sel_hi:[1,0,1]
	v_pk_fma_f32 v[82:83], v[158:159], s[28:29], v[82:83] op_sel_hi:[1,0,1]
	v_add_u32_e32 v189, 0x80000, v186
	global_load_dwordx2 v[182:183], v187, s[42:43] offset:1024
	global_load_dwordx4 v[144:147], v189, s[22:23]
	global_load_dwordx4 v[148:151], v189, s[22:23] offset:64
	global_load_dwordx4 v[152:155], v189, s[22:23] offset:512
	global_load_dwordx4 v[156:159], v189, s[22:23] offset:576
	v_add_u32_e32 v190, 0x20000, v186
	global_store_dwordx4 v190, v[92:95], s[18:19]
	global_store_dwordx4 v190, v[88:91], s[18:19] offset:64
	global_store_dwordx4 v190, v[84:87], s[18:19] offset:512
	global_store_dwordx4 v190, v[80:83], s[18:19] offset:576
	s_waitcnt vmcnt(13)
;     __device__ __forceinline__ void operator()(const Acc& acc, const Unit& u, int wv) const {
;     ...
;             for (int q = 0; q < 2; ++q) { const int i = pr * 2 + q, row = row0 + (i >> 2) * HALF + (i & 3) * 16; const size_t ro = (size_t)row * 1024 + col0;
;                 st[q] = (f32x2){0.f, 1.f}; if (ST) st[q] = ST[row];
; #pragma unroll
;                 for (int c4 = 0; c4 < 4; ++c4) xi[q][c4] = *(const f32x4*)(XIN + ro + (c4 >> 1) * HALF + (c4 & 1) * 16); }
; #pragma unroll
;             for (int q = 0; q < 2; ++q) { const int i = pr * 2 + q, row = row0 + (i >> 2) * HALF + (i & 3) * 16; const size_t ro = (size_t)row * 1024 + col0;
; #pragma unroll
;                 for (int c4 = 0; c4 < 4; ++c4) { const int co = (c4 >> 1) * HALF + (c4 & 1) * 16; f32x4 x = xi[q][c4];
;                     if (ST) { const f32x4 g = *(const f32x4*)(G + col0 + co), b = *(const f32x4*)(B + col0 + co); x = (x - st[q][0]) * st[q][1] * g + b; }
;                     if (!nowrite) *(f32x4*)(XRES + ro + co) = acc[i >> 2][c4 >> 1][i & 3][c4 & 1] + x * ALPHA; } }
	v_mov_b32_e32 v194, v185
	v_mov_b32_e32 v195, v185
	v_sub_f32_e32 v160, v160, v184
	v_sub_f32_e32 v161, v161, v184
	v_sub_f32_e32 v162, v162, v184
	v_sub_f32_e32 v163, v163, v184
	v_pk_mul_f32 v[160:161], v[194:195], v[160:161]
	v_pk_mul_f32 v[162:163], v[194:195], v[162:163]
	v_pk_mul_f32 v[160:161], v[160:161], v[128:129]
	v_pk_mul_f32 v[162:163], v[162:163], v[130:131]
	v_pk_fma_f32 v[76:77], v[160:161], s[28:29], v[76:77] op_sel_hi:[1,0,1]
	v_pk_fma_f32 v[78:79], v[162:163], s[28:29], v[78:79] op_sel_hi:[1,0,1]
	v_sub_f32_e32 v170, v170, v184
	v_sub_f32_e32 v171, v171, v184
	v_sub_f32_e32 v172, v172, v184
	v_sub_f32_e32 v173, v173, v184
	v_pk_mul_f32 v[170:171], v[194:195], v[170:171]
	v_pk_mul_f32 v[172:173], v[194:195], v[172:173]
	v_pk_mul_f32 v[170:171], v[170:171], v[132:133]
	v_pk_mul_f32 v[172:173], v[172:173], v[134:135]
	v_pk_fma_f32 v[72:73], v[170:171], s[28:29], v[72:73] op_sel_hi:[1,0,1]
	v_pk_fma_f32 v[74:75], v[172:173], s[28:29], v[74:75] op_sel_hi:[1,0,1]
	v_sub_f32_e32 v174, v174, v184
	v_sub_f32_e32 v175, v175, v184
	v_sub_f32_e32 v176, v176, v184
	v_sub_f32_e32 v177, v177, v184
	v_pk_mul_f32 v[174:175], v[194:195], v[174:175]
	v_pk_mul_f32 v[176:177], v[194:195], v[176:177]
	v_pk_mul_f32 v[174:175], v[174:175], v[136:137]
	v_pk_mul_f32 v[176:177], v[176:177], v[138:139]
	v_pk_fma_f32 v[68:69], v[174:175], s[28:29], v[68:69] op_sel_hi:[1,0,1]
	v_pk_fma_f32 v[70:71], v[176:177], s[28:29], v[70:71] op_sel_hi:[1,0,1]
	v_sub_f32_e32 v178, v178, v184
	v_sub_f32_e32 v179, v179, v184
	v_sub_f32_e32 v180, v180, v184
	v_sub_f32_e32 v181, v181, v184
	v_pk_mul_f32 v[178:179], v[194:195], v[178:179]
	v_pk_mul_f32 v[180:181], v[194:195], v[180:181]
	v_pk_mul_f32 v[178:179], v[178:179], v[140:141]
	v_pk_mul_f32 v[180:181], v[180:181], v[142:143]
	v_pk_fma_f32 v[64:65], v[178:179], s[28:29], v[64:65] op_sel_hi:[1,0,1]
	v_pk_fma_f32 v[66:67], v[180:181], s[28:29], v[66:67] op_sel_hi:[1,0,1]
	v_add_u32_e32 v189, 0x90000, v186
	global_load_dwordx2 v[184:185], v187, s[42:43] offset:1152
	global_load_dwordx4 v[160:163], v189, s[22:23]
	global_load_dwordx4 v[170:173], v189, s[22:23] offset:64
	global_load_dwordx4 v[174:177], v189, s[22:23] offset:512
	global_load_dwordx4 v[178:181], v189, s[22:23] offset:576
	v_add_u32_e32 v190, 0x30000, v186
	global_store_dwordx4 v190, v[76:79], s[18:19]
	global_store_dwordx4 v190, v[72:75], s[18:19] offset:64
	global_store_dwordx4 v190, v[68:71], s[18:19] offset:512
	global_store_dwordx4 v190, v[64:67], s[18:19] offset:576
	s_waitcnt vmcnt(13)
	v_mov_b32_e32 v194, v183
	v_mov_b32_e32 v195, v183
	v_sub_f32_e32 v144, v144, v182
	v_sub_f32_e32 v145, v145, v182
	v_sub_f32_e32 v146, v146, v182
	v_sub_f32_e32 v147, v147, v182
	v_pk_mul_f32 v[144:145], v[194:195], v[144:145]
	v_pk_mul_f32 v[146:147], v[194:195], v[146:147]
	v_pk_mul_f32 v[144:145], v[144:145], v[128:129]
	v_pk_mul_f32 v[146:147], v[146:147], v[130:131]
	v_pk_fma_f32 v[60:61], v[144:145], s[28:29], v[60:61] op_sel_hi:[1,0,1]
	v_pk_fma_f32 v[62:63], v[146:147], s[28:29], v[62:63] op_sel_hi:[1,0,1]
	v_sub_f32_e32 v148, v148, v182
	v_sub_f32_e32 v149, v149, v182
	v_sub_f32_e32 v150, v150, v182
	v_sub_f32_e32 v151, v151, v182
	v_pk_mul_f32 v[148:149], v[194:195], v[148:149]
	v_pk_mul_f32 v[150:151], v[194:195], v[150:151]
	v_pk_mul_f32 v[148:149], v[148:149], v[132:133]
	v_pk_mul_f32 v[150:151], v[150:151], v[134:135]
	v_pk_fma_f32 v[56:57], v[148:149], s[28:29], v[56:57] op_sel_hi:[1,0,1]
	v_pk_fma_f32 v[58:59], v[150:151], s[28:29], v[58:59] op_sel_hi:[1,0,1]
	v_sub_f32_e32 v152, v152, v182
	v_sub_f32_e32 v153, v153, v182
	v_sub_f32_e32 v154, v154, v182
	v_sub_f32_e32 v155, v155, v182
	v_pk_mul_f32 v[152:153], v[194:195], v[152:153]
	v_pk_mul_f32 v[154:155], v[194:195], v[154:155]
	v_pk_mul_f32 v[152:153], v[152:153], v[136:137]
	v_pk_mul_f32 v[154:155], v[154:155], v[138:139]
	v_pk_fma_f32 v[52:53], v[152:153], s[28:29], v[52:53] op_sel_hi:[1,0,1]
	v_pk_fma_f32 v[54:55], v[154:155], s[28:29], v[54:55] op_sel_hi:[1,0,1]
	v_sub_f32_e32 v156, v156, v182
	v_sub_f32_e32 v157, v157, v182
	v_sub_f32_e32 v158, v158, v182
	v_sub_f32_e32 v159, v159, v182
	v_pk_mul_f32 v[156:157], v[194:195], v[156:157]
	v_pk_mul_f32 v[158:159], v[194:195], v[158:159]
	v_pk_mul_f32 v[156:157], v[156:157], v[140:141]
	v_pk_mul_f32 v[158:159], v[158:159], v[142:143]
	v_pk_fma_f32 v[48:49], v[156:157], s[28:29], v[48:49] op_sel_hi:[1,0,1]
	v_pk_fma_f32 v[50:51], v[158:159], s[28:29], v[50:51] op_sel_hi:[1,0,1]
	v_add_u32_e32 v189, 0xa0000, v186
	global_load_dwordx2 v[182:183], v187, s[42:43] offset:1280
	global_load_dwordx4 v[144:147], v189, s[22:23]
	global_load_dwordx4 v[148:151], v189, s[22:23] offset:64
	global_load_dwordx4 v[152:155], v189, s[22:23] offset:512
	global_load_dwordx4 v[156:159], v189, s[22:23] offset:576
	v_add_u32_e32 v190, 0x80000, v186
	global_store_dwordx4 v190, v[60:63], s[18:19]
	global_store_dwordx4 v190, v[56:59], s[18:19] offset:64
	global_store_dwordx4 v190, v[52:55], s[18:19] offset:512
	global_store_dwordx4 v190, v[48:51], s[18:19] offset:576
	s_waitcnt vmcnt(13)
;     __device__ __forceinline__ void operator()(const Acc& acc, const Unit& u, int wv) const {
;     ...
;             for (int q = 0; q < 2; ++q) { const int i = pr * 2 + q, row = row0 + (i >> 2) * HALF + (i & 3) * 16; const size_t ro = (size_t)row * 1024 + col0;
;                 st[q] = (f32x2){0.f, 1.f}; if (ST) st[q] = ST[row];
; #pragma unroll
;                 for (int c4 = 0; c4 < 4; ++c4) xi[q][c4] = *(const f32x4*)(XIN + ro + (c4 >> 1) * HALF + (c4 & 1) * 16); }
; #pragma unroll
;             for (int q = 0; q < 2; ++q) { const int i = pr * 2 + q, row = row0 + (i >> 2) * HALF + (i & 3) * 16; const size_t ro = (size_t)row * 1024 + col0;
; #pragma unroll
;                 for (int c4 = 0; c4 < 4; ++c4) { const int co = (c4 >> 1) * HALF + (c4 & 1) * 16; f32x4 x = xi[q][c4];
;                     if (ST) { const f32x4 g = *(const f32x4*)(G + col0 + co), b = *(const f32x4*)(B + col0 + co); x = (x - st[q][0]) * st[q][1] * g + b; }
;                     if (!nowrite) *(f32x4*)(XRES + ro + co) = acc[i >> 2][c4 >> 1][i & 3][c4 & 1] + x * ALPHA; } }
	v_mov_b32_e32 v194, v185
	v_mov_b32_e32 v195, v185
	v_sub_f32_e32 v160, v160, v184
	v_sub_f32_e32 v161, v161, v184
	v_sub_f32_e32 v162, v162, v184
	v_sub_f32_e32 v163, v163, v184
	v_pk_mul_f32 v[160:161], v[194:195], v[160:161]
	v_pk_mul_f32 v[162:163], v[194:195], v[162:163]
	v_pk_mul_f32 v[160:161], v[160:161], v[128:129]
	v_pk_mul_f32 v[162:163], v[162:163], v[130:131]
	v_pk_fma_f32 v[44:45], v[160:161], s[28:29], v[44:45] op_sel_hi:[1,0,1]
	v_pk_fma_f32 v[46:47], v[162:163], s[28:29], v[46:47] op_sel_hi:[1,0,1]
	v_sub_f32_e32 v170, v170, v184
	v_sub_f32_e32 v171, v171, v184
	v_sub_f32_e32 v172, v172, v184
	v_sub_f32_e32 v173, v173, v184
	v_pk_mul_f32 v[170:171], v[194:195], v[170:171]
	v_pk_mul_f32 v[172:173], v[194:195], v[172:173]
	v_pk_mul_f32 v[170:171], v[170:171], v[132:133]
	v_pk_mul_f32 v[172:173], v[172:173], v[134:135]
	v_pk_fma_f32 v[40:41], v[170:171], s[28:29], v[40:41] op_sel_hi:[1,0,1]
	v_pk_fma_f32 v[42:43], v[172:173], s[28:29], v[42:43] op_sel_hi:[1,0,1]
	v_sub_f32_e32 v174, v174, v184
	v_sub_f32_e32 v175, v175, v184
	v_sub_f32_e32 v176, v176, v184
	v_sub_f32_e32 v177, v177, v184
	v_pk_mul_f32 v[174:175], v[194:195], v[174:175]
	v_pk_mul_f32 v[176:177], v[194:195], v[176:177]
	v_pk_mul_f32 v[174:175], v[174:175], v[136:137]
	v_pk_mul_f32 v[176:177], v[176:177], v[138:139]
	v_pk_fma_f32 v[36:37], v[174:175], s[28:29], v[36:37] op_sel_hi:[1,0,1]
	v_pk_fma_f32 v[38:39], v[176:177], s[28:29], v[38:39] op_sel_hi:[1,0,1]
	v_sub_f32_e32 v178, v178, v184
	v_sub_f32_e32 v179, v179, v184
	v_sub_f32_e32 v180, v180, v184
	v_sub_f32_e32 v181, v181, v184
	v_pk_mul_f32 v[178:179], v[194:195], v[178:179]
	v_pk_mul_f32 v[180:181], v[194:195], v[180:181]
	v_pk_mul_f32 v[178:179], v[178:179], v[140:141]
	v_pk_mul_f32 v[180:181], v[180:181], v[142:143]
	v_pk_fma_f32 v[32:33], v[178:179], s[28:29], v[32:33] op_sel_hi:[1,0,1]
	v_pk_fma_f32 v[34:35], v[180:181], s[28:29], v[34:35] op_sel_hi:[1,0,1]
	v_add_u32_e32 v189, 0xb0000, v186
	global_load_dwordx2 v[184:185], v187, s[42:43] offset:1408
	global_load_dwordx4 v[160:163], v189, s[22:23]
	global_load_dwordx4 v[170:173], v189, s[22:23] offset:64
	global_load_dwordx4 v[174:177], v189, s[22:23] offset:512
	global_load_dwordx4 v[178:181], v189, s[22:23] offset:576
	v_add_u32_e32 v190, 0x90000, v186
	global_store_dwordx4 v190, v[44:47], s[18:19]
	global_store_dwordx4 v190, v[40:43], s[18:19] offset:64
	global_store_dwordx4 v190, v[36:39], s[18:19] offset:512
	global_store_dwordx4 v190, v[32:35], s[18:19] offset:576
	s_waitcnt vmcnt(13)
	v_mov_b32_e32 v194, v183
	v_mov_b32_e32 v195, v183
	v_sub_f32_e32 v144, v144, v182
	v_sub_f32_e32 v145, v145, v182
	v_sub_f32_e32 v146, v146, v182
	v_sub_f32_e32 v147, v147, v182
	v_pk_mul_f32 v[144:145], v[194:195], v[144:145]
	v_pk_mul_f32 v[146:147], v[194:195], v[146:147]
	v_pk_mul_f32 v[144:145], v[144:145], v[128:129]
	v_pk_mul_f32 v[146:147], v[146:147], v[130:131]
	v_pk_fma_f32 v[28:29], v[144:145], s[28:29], v[28:29] op_sel_hi:[1,0,1]
	v_pk_fma_f32 v[30:31], v[146:147], s[28:29], v[30:31] op_sel_hi:[1,0,1]
	v_sub_f32_e32 v148, v148, v182
	v_sub_f32_e32 v149, v149, v182
	v_sub_f32_e32 v150, v150, v182
	v_sub_f32_e32 v151, v151, v182
	v_pk_mul_f32 v[148:149], v[194:195], v[148:149]
	v_pk_mul_f32 v[150:151], v[194:195], v[150:151]
	v_pk_mul_f32 v[148:149], v[148:149], v[132:133]
	v_pk_mul_f32 v[150:151], v[150:151], v[134:135]
	v_pk_fma_f32 v[24:25], v[148:149], s[28:29], v[24:25] op_sel_hi:[1,0,1]
	v_pk_fma_f32 v[26:27], v[150:151], s[28:29], v[26:27] op_sel_hi:[1,0,1]
	v_sub_f32_e32 v152, v152, v182
	v_sub_f32_e32 v153, v153, v182
	v_sub_f32_e32 v154, v154, v182
	v_sub_f32_e32 v155, v155, v182
	v_pk_mul_f32 v[152:153], v[194:195], v[152:153]
	v_pk_mul_f32 v[154:155], v[194:195], v[154:155]
	v_pk_mul_f32 v[152:153], v[152:153], v[136:137]
	v_pk_mul_f32 v[154:155], v[154:155], v[138:139]
	v_pk_fma_f32 v[20:21], v[152:153], s[28:29], v[20:21] op_sel_hi:[1,0,1]
	v_pk_fma_f32 v[22:23], v[154:155], s[28:29], v[22:23] op_sel_hi:[1,0,1]
	v_sub_f32_e32 v156, v156, v182
	v_sub_f32_e32 v157, v157, v182
	v_sub_f32_e32 v158, v158, v182
	v_sub_f32_e32 v159, v159, v182
	v_pk_mul_f32 v[156:157], v[194:195], v[156:157]
	v_pk_mul_f32 v[158:159], v[194:195], v[158:159]
	v_pk_mul_f32 v[156:157], v[156:157], v[140:141]
	v_pk_mul_f32 v[158:159], v[158:159], v[142:143]
	v_pk_fma_f32 v[16:17], v[156:157], s[28:29], v[16:17] op_sel_hi:[1,0,1]
	v_pk_fma_f32 v[18:19], v[158:159], s[28:29], v[18:19] op_sel_hi:[1,0,1]
	v_add_u32_e32 v190, 0xa0000, v186
	global_store_dwordx4 v190, v[28:31], s[18:19]
	global_store_dwordx4 v190, v[24:27], s[18:19] offset:64
	global_store_dwordx4 v190, v[20:23], s[18:19] offset:512
	global_store_dwordx4 v190, v[16:19], s[18:19] offset:576
	s_waitcnt vmcnt(8)
	v_mov_b32_e32 v194, v185
	v_mov_b32_e32 v195, v185
	v_sub_f32_e32 v160, v160, v184
	v_sub_f32_e32 v161, v161, v184
	v_sub_f32_e32 v162, v162, v184
	v_sub_f32_e32 v163, v163, v184
	v_pk_mul_f32 v[160:161], v[194:195], v[160:161]
	v_pk_mul_f32 v[162:163], v[194:195], v[162:163]
	v_pk_mul_f32 v[160:161], v[160:161], v[128:129]
	v_pk_mul_f32 v[162:163], v[162:163], v[130:131]
	v_pk_fma_f32 v[12:13], v[160:161], s[28:29], v[12:13] op_sel_hi:[1,0,1]
	v_pk_fma_f32 v[14:15], v[162:163], s[28:29], v[14:15] op_sel_hi:[1,0,1]
	v_sub_f32_e32 v170, v170, v184
	v_sub_f32_e32 v171, v171, v184
	v_sub_f32_e32 v172, v172, v184
	v_sub_f32_e32 v173, v173, v184
	v_pk_mul_f32 v[170:171], v[194:195], v[170:171]
	v_pk_mul_f32 v[172:173], v[194:195], v[172:173]
	v_pk_mul_f32 v[170:171], v[170:171], v[132:133]
	v_pk_mul_f32 v[172:173], v[172:173], v[134:135]
	v_pk_fma_f32 v[8:9], v[170:171], s[28:29], v[8:9] op_sel_hi:[1,0,1]
	v_pk_fma_f32 v[10:11], v[172:173], s[28:29], v[10:11] op_sel_hi:[1,0,1]
	v_sub_f32_e32 v174, v174, v184
	v_sub_f32_e32 v175, v175, v184
	v_sub_f32_e32 v176, v176, v184
	v_sub_f32_e32 v177, v177, v184
	v_pk_mul_f32 v[174:175], v[194:195], v[174:175]
	v_pk_mul_f32 v[176:177], v[194:195], v[176:177]
	v_pk_mul_f32 v[174:175], v[174:175], v[136:137]
	v_pk_mul_f32 v[176:177], v[176:177], v[138:139]
	v_pk_fma_f32 v[4:5], v[174:175], s[28:29], v[4:5] op_sel_hi:[1,0,1]
	v_pk_fma_f32 v[6:7], v[176:177], s[28:29], v[6:7] op_sel_hi:[1,0,1]
	v_sub_f32_e32 v178, v178, v184
	v_sub_f32_e32 v179, v179, v184
	v_sub_f32_e32 v180, v180, v184
	v_sub_f32_e32 v181, v181, v184
	v_pk_mul_f32 v[178:179], v[194:195], v[178:179]
	v_pk_mul_f32 v[180:181], v[194:195], v[180:181]
	v_pk_mul_f32 v[178:179], v[178:179], v[140:141]
	v_pk_mul_f32 v[180:181], v[180:181], v[142:143]
	v_pk_fma_f32 v[0:1], v[178:179], s[28:29], v[0:1] op_sel_hi:[1,0,1]
	v_pk_fma_f32 v[2:3], v[180:181], s[28:29], v[2:3] op_sel_hi:[1,0,1]
	v_add_u32_e32 v190, 0xb0000, v186
	global_store_dwordx4 v190, v[12:15], s[18:19]
	global_store_dwordx4 v190, v[8:11], s[18:19] offset:64
	global_store_dwordx4 v190, v[4:7], s[18:19] offset:512
	global_store_dwordx4 v190, v[0:3], s[18:19] offset:576
	s_branch .LBB0_416
;     __device__ __forceinline__ void operator()(const Acc& acc, const Unit& u, int wv) const {
;     ...
;             for (int q = 0; q < 2; ++q) { const int i = pr * 2 + q, row = row0 + (i >> 2) * HALF + (i & 3) * 16; const size_t ro = (size_t)row * 1024 + col0;
;                 st[q] = (f32x2){0.f, 1.f}; if (ST) st[q] = ST[row];
; #pragma unroll
;                 for (int c4 = 0; c4 < 4; ++c4) xi[q][c4] = *(const f32x4*)(XIN + ro + (c4 >> 1) * HALF + (c4 & 1) * 16); }
; #pragma unroll
;             for (int q = 0; q < 2; ++q) { const int i = pr * 2 + q, row = row0 + (i >> 2) * HALF + (i & 3) * 16; const size_t ro = (size_t)row * 1024 + col0;
; #pragma unroll
;                 for (int c4 = 0; c4 < 4; ++c4) { const int co = (c4 >> 1) * HALF + (c4 & 1) * 16; f32x4 x = xi[q][c4];
;                     if (ST) { const f32x4 g = *(const f32x4*)(G + col0 + co), b = *(const f32x4*)(B + col0 + co); x = (x - st[q][0]) * st[q][1] * g + b; }
;                     if (!nowrite) *(f32x4*)(XRES + ro + co) = acc[i >> 2][c4 >> 1][i & 3][c4 & 1] + x * ALPHA; } }
.Lepi_res_nost:
	global_load_dwordx4 v[144:147], v186, s[22:23]
	global_load_dwordx4 v[148:151], v186, s[22:23] offset:64
	global_load_dwordx4 v[152:155], v186, s[22:23] offset:512
	global_load_dwordx4 v[156:159], v186, s[22:23] offset:576
	v_add_u32_e32 v189, 0x10000, v186
	global_load_dwordx4 v[160:163], v189, s[22:23]
	global_load_dwordx4 v[170:173], v189, s[22:23] offset:64
	global_load_dwordx4 v[174:177], v189, s[22:23] offset:512
	global_load_dwordx4 v[178:181], v189, s[22:23] offset:576
	s_waitcnt vmcnt(4)
	v_pk_fma_f32 v[124:125], v[144:145], s[28:29], v[124:125] op_sel_hi:[1,0,1]
	v_pk_fma_f32 v[126:127], v[146:147], s[28:29], v[126:127] op_sel_hi:[1,0,1]
	v_pk_fma_f32 v[120:121], v[148:149], s[28:29], v[120:121] op_sel_hi:[1,0,1]
	v_pk_fma_f32 v[122:123], v[150:151], s[28:29], v[122:123] op_sel_hi:[1,0,1]
	v_pk_fma_f32 v[116:117], v[152:153], s[28:29], v[116:117] op_sel_hi:[1,0,1]
	v_pk_fma_f32 v[118:119], v[154:155], s[28:29], v[118:119] op_sel_hi:[1,0,1]
	v_pk_fma_f32 v[112:113], v[156:157], s[28:29], v[112:113] op_sel_hi:[1,0,1]
	v_pk_fma_f32 v[114:115], v[158:159], s[28:29], v[114:115] op_sel_hi:[1,0,1]
	v_add_u32_e32 v189, 0x20000, v186
	global_load_dwordx4 v[144:147], v189, s[22:23]
	global_load_dwordx4 v[148:151], v189, s[22:23] offset:64
	global_load_dwordx4 v[152:155], v189, s[22:23] offset:512
	global_load_dwordx4 v[156:159], v189, s[22:23] offset:576
	global_store_dwordx4 v186, v[124:127], s[18:19]
	global_store_dwordx4 v186, v[120:123], s[18:19] offset:64
	global_store_dwordx4 v186, v[116:119], s[18:19] offset:512
	global_store_dwordx4 v186, v[112:115], s[18:19] offset:576
	s_waitcnt vmcnt(8)
	v_pk_fma_f32 v[108:109], v[160:161], s[28:29], v[108:109] op_sel_hi:[1,0,1]
	v_pk_fma_f32 v[110:111], v[162:163], s[28:29], v[110:111] op_sel_hi:[1,0,1]
	v_pk_fma_f32 v[104:105], v[170:171], s[28:29], v[104:105] op_sel_hi:[1,0,1]
	v_pk_fma_f32 v[106:107], v[172:173], s[28:29], v[106:107] op_sel_hi:[1,0,1]
	v_pk_fma_f32 v[100:101], v[174:175], s[28:29], v[100:101] op_sel_hi:[1,0,1]
	v_pk_fma_f32 v[102:103], v[176:177], s[28:29], v[102:103] op_sel_hi:[1,0,1]
	v_pk_fma_f32 v[96:97], v[178:179], s[28:29], v[96:97] op_sel_hi:[1,0,1]
	v_pk_fma_f32 v[98:99], v[180:181], s[28:29], v[98:99] op_sel_hi:[1,0,1]
	v_add_u32_e32 v189, 0x30000, v186
	global_load_dwordx4 v[160:163], v189, s[22:23]
	global_load_dwordx4 v[170:173], v189, s[22:23] offset:64
	global_load_dwordx4 v[174:177], v189, s[22:23] offset:512
	global_load_dwordx4 v[178:181], v189, s[22:23] offset:576
	v_add_u32_e32 v190, 0x10000, v186
	global_store_dwordx4 v190, v[108:111], s[18:19]
	global_store_dwordx4 v190, v[104:107], s[18:19] offset:64
	global_store_dwordx4 v190, v[100:103], s[18:19] offset:512
	global_store_dwordx4 v190, v[96:99], s[18:19] offset:576
	s_waitcnt vmcnt(12)
	v_pk_fma_f32 v[92:93], v[144:145], s[28:29], v[92:93] op_sel_hi:[1,0,1]
	v_pk_fma_f32 v[94:95], v[146:147], s[28:29], v[94:95] op_sel_hi:[1,0,1]
	v_pk_fma_f32 v[88:89], v[148:149], s[28:29], v[88:89] op_sel_hi:[1,0,1]
	v_pk_fma_f32 v[90:91], v[150:151], s[28:29], v[90:91] op_sel_hi:[1,0,1]
	v_pk_fma_f32 v[84:85], v[152:153], s[28:29], v[84:85] op_sel_hi:[1,0,1]
	v_pk_fma_f32 v[86:87], v[154:155], s[28:29], v[86:87] op_sel_hi:[1,0,1]
	v_pk_fma_f32 v[80:81], v[156:157], s[28:29], v[80:81] op_sel_hi:[1,0,1]
	v_pk_fma_f32 v[82:83], v[158:159], s[28:29], v[82:83] op_sel_hi:[1,0,1]
	v_add_u32_e32 v189, 0x80000, v186
	global_load_dwordx4 v[144:147], v189, s[22:23]
	global_load_dwordx4 v[148:151], v189, s[22:23] offset:64
	global_load_dwordx4 v[152:155], v189, s[22:23] offset:512
	global_load_dwordx4 v[156:159], v189, s[22:23] offset:576
	v_add_u32_e32 v190, 0x20000, v186
	global_store_dwordx4 v190, v[92:95], s[18:19]
	global_store_dwordx4 v190, v[88:91], s[18:19] offset:64
	global_store_dwordx4 v190, v[84:87], s[18:19] offset:512
	global_store_dwordx4 v190, v[80:83], s[18:19] offset:576
	s_waitcnt vmcnt(12)
	v_pk_fma_f32 v[76:77], v[160:161], s[28:29], v[76:77] op_sel_hi:[1,0,1]
	v_pk_fma_f32 v[78:79], v[162:163], s[28:29], v[78:79] op_sel_hi:[1,0,1]
	v_pk_fma_f32 v[72:73], v[170:171], s[28:29], v[72:73] op_sel_hi:[1,0,1]
	v_pk_fma_f32 v[74:75], v[172:173], s[28:29], v[74:75] op_sel_hi:[1,0,1]
	v_pk_fma_f32 v[68:69], v[174:175], s[28:29], v[68:69] op_sel_hi:[1,0,1]
	v_pk_fma_f32 v[70:71], v[176:177], s[28:29], v[70:71] op_sel_hi:[1,0,1]
	v_pk_fma_f32 v[64:65], v[178:179], s[28:29], v[64:65] op_sel_hi:[1,0,1]
	v_pk_fma_f32 v[66:67], v[180:181], s[28:29], v[66:67] op_sel_hi:[1,0,1]
	v_add_u32_e32 v189, 0x90000, v186
	global_load_dwordx4 v[160:163], v189, s[22:23]
	global_load_dwordx4 v[170:173], v189, s[22:23] offset:64
	global_load_dwordx4 v[174:177], v189, s[22:23] offset:512
	global_load_dwordx4 v[178:181], v189, s[22:23] offset:576
	v_add_u32_e32 v190, 0x30000, v186
	global_store_dwordx4 v190, v[76:79], s[18:19]
	global_store_dwordx4 v190, v[72:75], s[18:19] offset:64
	global_store_dwordx4 v190, v[68:71], s[18:19] offset:512
	global_store_dwordx4 v190, v[64:67], s[18:19] offset:576
	s_waitcnt vmcnt(12)
;     __device__ __forceinline__ void operator()(const Acc& acc, const Unit& u, int wv) const {
;     ...
;             for (int q = 0; q < 2; ++q) { const int i = pr * 2 + q, row = row0 + (i >> 2) * HALF + (i & 3) * 16; const size_t ro = (size_t)row * 1024 + col0;
;                 st[q] = (f32x2){0.f, 1.f}; if (ST) st[q] = ST[row];
; #pragma unroll
;                 for (int c4 = 0; c4 < 4; ++c4) xi[q][c4] = *(const f32x4*)(XIN + ro + (c4 >> 1) * HALF + (c4 & 1) * 16); }
; #pragma unroll
;             for (int q = 0; q < 2; ++q) { const int i = pr * 2 + q, row = row0 + (i >> 2) * HALF + (i & 3) * 16; const size_t ro = (size_t)row * 1024 + col0;
; #pragma unroll
;                 for (int c4 = 0; c4 < 4; ++c4) { const int co = (c4 >> 1) * HALF + (c4 & 1) * 16; f32x4 x = xi[q][c4];
;                     if (ST) { const f32x4 g = *(const f32x4*)(G + col0 + co), b = *(const f32x4*)(B + col0 + co); x = (x - st[q][0]) * st[q][1] * g + b; }
;                     if (!nowrite) *(f32x4*)(XRES + ro + co) = acc[i >> 2][c4 >> 1][i & 3][c4 & 1] + x * ALPHA; } }
	v_pk_fma_f32 v[60:61], v[144:145], s[28:29], v[60:61] op_sel_hi:[1,0,1]
	v_pk_fma_f32 v[62:63], v[146:147], s[28:29], v[62:63] op_sel_hi:[1,0,1]
	v_pk_fma_f32 v[56:57], v[148:149], s[28:29], v[56:57] op_sel_hi:[1,0,1]
	v_pk_fma_f32 v[58:59], v[150:151], s[28:29], v[58:59] op_sel_hi:[1,0,1]
	v_pk_fma_f32 v[52:53], v[152:153], s[28:29], v[52:53] op_sel_hi:[1,0,1]
	v_pk_fma_f32 v[54:55], v[154:155], s[28:29], v[54:55] op_sel_hi:[1,0,1]
	v_pk_fma_f32 v[48:49], v[156:157], s[28:29], v[48:49] op_sel_hi:[1,0,1]
	v_pk_fma_f32 v[50:51], v[158:159], s[28:29], v[50:51] op_sel_hi:[1,0,1]
	v_add_u32_e32 v189, 0xa0000, v186
	global_load_dwordx4 v[144:147], v189, s[22:23]
	global_load_dwordx4 v[148:151], v189, s[22:23] offset:64
	global_load_dwordx4 v[152:155], v189, s[22:23] offset:512
	global_load_dwordx4 v[156:159], v189, s[22:23] offset:576
	v_add_u32_e32 v190, 0x80000, v186
	global_store_dwordx4 v190, v[60:63], s[18:19]
	global_store_dwordx4 v190, v[56:59], s[18:19] offset:64
	global_store_dwordx4 v190, v[52:55], s[18:19] offset:512
	global_store_dwordx4 v190, v[48:51], s[18:19] offset:576
	s_waitcnt vmcnt(12)
	v_pk_fma_f32 v[44:45], v[160:161], s[28:29], v[44:45] op_sel_hi:[1,0,1]
	v_pk_fma_f32 v[46:47], v[162:163], s[28:29], v[46:47] op_sel_hi:[1,0,1]
	v_pk_fma_f32 v[40:41], v[170:171], s[28:29], v[40:41] op_sel_hi:[1,0,1]
	v_pk_fma_f32 v[42:43], v[172:173], s[28:29], v[42:43] op_sel_hi:[1,0,1]
	v_pk_fma_f32 v[36:37], v[174:175], s[28:29], v[36:37] op_sel_hi:[1,0,1]
	v_pk_fma_f32 v[38:39], v[176:177], s[28:29], v[38:39] op_sel_hi:[1,0,1]
	v_pk_fma_f32 v[32:33], v[178:179], s[28:29], v[32:33] op_sel_hi:[1,0,1]
	v_pk_fma_f32 v[34:35], v[180:181], s[28:29], v[34:35] op_sel_hi:[1,0,1]
	v_add_u32_e32 v189, 0xb0000, v186
	global_load_dwordx4 v[160:163], v189, s[22:23]
	global_load_dwordx4 v[170:173], v189, s[22:23] offset:64
	global_load_dwordx4 v[174:177], v189, s[22:23] offset:512
	global_load_dwordx4 v[178:181], v189, s[22:23] offset:576
	v_add_u32_e32 v190, 0x90000, v186
	global_store_dwordx4 v190, v[44:47], s[18:19]
	global_store_dwordx4 v190, v[40:43], s[18:19] offset:64
	global_store_dwordx4 v190, v[36:39], s[18:19] offset:512
	global_store_dwordx4 v190, v[32:35], s[18:19] offset:576
	s_waitcnt vmcnt(12)
	v_pk_fma_f32 v[28:29], v[144:145], s[28:29], v[28:29] op_sel_hi:[1,0,1]
	v_pk_fma_f32 v[30:31], v[146:147], s[28:29], v[30:31] op_sel_hi:[1,0,1]
	v_pk_fma_f32 v[24:25], v[148:149], s[28:29], v[24:25] op_sel_hi:[1,0,1]
	v_pk_fma_f32 v[26:27], v[150:151], s[28:29], v[26:27] op_sel_hi:[1,0,1]
	v_pk_fma_f32 v[20:21], v[152:153], s[28:29], v[20:21] op_sel_hi:[1,0,1]
	v_pk_fma_f32 v[22:23], v[154:155], s[28:29], v[22:23] op_sel_hi:[1,0,1]
	v_pk_fma_f32 v[16:17], v[156:157], s[28:29], v[16:17] op_sel_hi:[1,0,1]
	v_pk_fma_f32 v[18:19], v[158:159], s[28:29], v[18:19] op_sel_hi:[1,0,1]
	v_add_u32_e32 v190, 0xa0000, v186
	global_store_dwordx4 v190, v[28:31], s[18:19]
	global_store_dwordx4 v190, v[24:27], s[18:19] offset:64
	global_store_dwordx4 v190, v[20:23], s[18:19] offset:512
	global_store_dwordx4 v190, v[16:19], s[18:19] offset:576
	s_waitcnt vmcnt(8)
	v_pk_fma_f32 v[12:13], v[160:161], s[28:29], v[12:13] op_sel_hi:[1,0,1]
	v_pk_fma_f32 v[14:15], v[162:163], s[28:29], v[14:15] op_sel_hi:[1,0,1]
	v_pk_fma_f32 v[8:9], v[170:171], s[28:29], v[8:9] op_sel_hi:[1,0,1]
	v_pk_fma_f32 v[10:11], v[172:173], s[28:29], v[10:11] op_sel_hi:[1,0,1]
	v_pk_fma_f32 v[4:5], v[174:175], s[28:29], v[4:5] op_sel_hi:[1,0,1]
	v_pk_fma_f32 v[6:7], v[176:177], s[28:29], v[6:7] op_sel_hi:[1,0,1]
	v_pk_fma_f32 v[0:1], v[178:179], s[28:29], v[0:1] op_sel_hi:[1,0,1]
	v_pk_fma_f32 v[2:3], v[180:181], s[28:29], v[2:3] op_sel_hi:[1,0,1]
	v_add_u32_e32 v190, 0xb0000, v186
	global_store_dwordx4 v190, v[12:15], s[18:19]
	global_store_dwordx4 v190, v[8:11], s[18:19] offset:64
	global_store_dwordx4 v190, v[4:7], s[18:19] offset:512
	global_store_dwordx4 v190, v[0:3], s[18:19] offset:576
	s_branch .LBB0_416
